# v27 + first K-iteration of every unit peeled with srcC=0 MFMAs; the 128 accumulator-zeroing v_movs per unit removed
# speedup vs baseline: 1.0124x; 1.0121x over previous
; #define PG8_STAGE(bufoff, gbase, voff) do { _Pragma("unroll") for (int _i = 0; _i < 2; ++_i) \
;         pg8_dma16((const char*)(gbase), (voff)[_i], ldsb + (unsigned)((bufoff) + _i * 8192)); } while (0)
; #define PG8_LDA(dst, b, h) do { _Pragma("unroll") for (int m = 0; m < 4; ++m) _Pragma("unroll") for (int k = 0; k < 2; ++k) dst[m][k] = *(const PG8_LAS bf16x8*)(lds + PG8_SA(b, h) + aoff + m * 2048 + k * 1024); } while (0)
; #define PG8_LDB(dst, b, h) do { _Pragma("unroll") for (int n = 0; n < 2; ++n) _Pragma("unroll") for (int k = 0; k < 2; ++k) dst[n][k] = *(const PG8_LAS bf16x8*)(lds + PG8_SB(b, h) + boff + n * 2048 + k * 1024); } while (0)
; #define PG8_MMA(ai, bj, At, Bt) do { __builtin_amdgcn_s_setprio(1); _Pragma("unroll") for (int m = 0; m < 4; ++m) _Pragma("unroll") for (int n = 0; n < 2; ++n) _Pragma("unroll") for (int k = 0; k < 2; ++k) \
;         acc[ai][bj][m][n] = __builtin_amdgcn_mfma_f32_16x16x32_bf16(Bt[n][k], At[m][k], acc[ai][bj][m][n], 0, 0, 0); __builtin_amdgcn_s_setprio(0); } while (0)
; #define PG8_WAIT_V(n) asm volatile("s_waitcnt vmcnt(" #n ")" ::: "memory")
; #define PG8_WAIT_L(n) asm volatile("s_waitcnt lgkmcnt(" #n ")" ::: "memory")
; #define PG8_BAR __builtin_amdgcn_s_barrier()
; #define PG8_SCHED __builtin_amdgcn_sched_barrier(0)
; template <class Epi, class Sched, bool ALIGN_EPI = false, bool SP2 = false>
; __device__ __forceinline__ void gemm_phase(PG8_LAS unsigned char* lds, const Gemm g, const Sched& S, const Epi& E) {
;     ...
;     for (int a = 0; a < 2; ++a)
; #pragma unroll
;         for (int b = 0; b < 2; ++b)
; #pragma unroll
;             for (int m = 0; m < 4; ++m)
; #pragma unroll
;                 for (int n = 0; n < 2; ++n) acc[a][b][m][n] = (f32x4){0.f, 0.f, 0.f, 0.f};
;     ...
;             PG8_LDB(B0, 0, 0); PG8_LDB(B1, 0, 1); PG8_SCHED; PG8_LDA(At, 0, 0); PG8_STAGE(PG8_SA(1, 1), a1 + hstep, voffA);
;             PG8_WAIT_V(8); PG8_WAIT_L(0); PG8_BAR; PG8_MMA(0, 0, At, B0); PG8_MMA(0, 1, At, B1); PG8_BAR; PG8_SCHED;
;             PG8_LDA(At, 0, 1); PG8_STAGE(PG8_SB(0, 0), b2, voffB); PG8_STAGE(PG8_SB(0, 1), b2 + hstep, voffB); PG8_STAGE(PG8_SA(0, 0), a2, voffA);
;             PG8_WAIT_V(8); PG8_WAIT_L(0); PG8_BAR; PG8_MMA(1, 0, At, B0); PG8_MMA(1, 1, At, B1); PG8_BAR; PG8_SCHED;
.LBB0_304:
	s_add_u32 s4, s36, s47
	s_addc_u32 s5, s37, 0
	s_add_u32 s72, s36, 0x100
	s_addc_u32 s95, s37, 0
	s_add_u32 vcc_lo, s12, 0x100
	s_addc_u32 vcc_hi, s13, 0
	s_add_u32 s10, s4, 0x80
	s_addc_u32 s11, s5, 0
	s_mov_b32 s12, 0
.Lpeel_body:
	ds_read_b128 v[128:131], v229
	ds_read_b128 v[132:135], v229 offset:1024
	ds_read_b128 v[136:139], v229 offset:2048
	ds_read_b128 v[140:143], v229 offset:3072
	ds_read_b128 v[144:147], v230
	ds_read_b128 v[152:155], v230 offset:1024
	ds_read_b128 v[156:159], v230 offset:2048
	ds_read_b128 v[160:163], v230 offset:3072
	s_add_i32 s58, s12, 2
	s_cmp_eq_u32 s77, s12
	s_cselect_b32 s40, s30, s72
	s_cselect_b32 s41, s31, s95
	s_cselect_b32 s36, s34, vcc_lo
	s_cselect_b32 s37, s35, vcc_hi
	s_add_u32 s12, s40, 0x80
	s_addc_u32 s13, s41, 0
	ds_read_b128 v[164:167], v208
	ds_read_b128 v[168:171], v208 offset:1024
	ds_read_b128 v[172:175], v208 offset:2048
	ds_read_b128 v[176:179], v208 offset:3072
	ds_read_b128 v[180:183], v208 offset:4096
	ds_read_b128 v[210:213], v208 offset:5120
	ds_read_b128 v[214:217], v208 offset:6144
	ds_read_b128 v[218:221], v208 offset:7168
	s_mov_b32 m0, s78
	s_nop 0
	global_load_lds_dwordx4 v148, s[10:11]
	s_mov_b32 m0, s80
	s_nop 0
	global_load_lds_dwordx4 v198, s[10:11]
	s_waitcnt vmcnt(8)
	s_waitcnt lgkmcnt(0)
	s_barrier
	s_setprio 1
	v_mfma_f32_16x16x32_bf16 v[124:127], v[128:131], v[164:167], 0
	v_mfma_f32_16x16x32_bf16 v[116:119], v[136:139], v[164:167], 0
	v_mfma_f32_16x16x32_bf16 v[108:111], v[128:131], v[172:175], 0
	v_mfma_f32_16x16x32_bf16 v[100:103], v[136:139], v[172:175], 0
	v_mfma_f32_16x16x32_bf16 v[92:95], v[128:131], v[180:183], 0
	v_mfma_f32_16x16x32_bf16 v[84:87], v[136:139], v[180:183], 0
	v_mfma_f32_16x16x32_bf16 v[76:79], v[128:131], v[214:217], 0
	v_mfma_f32_16x16x32_bf16 v[68:71], v[136:139], v[214:217], 0
	v_mfma_f32_16x16x32_bf16 v[124:127], v[132:135], v[168:171], v[124:127]
	v_mfma_f32_16x16x32_bf16 v[116:119], v[140:143], v[168:171], v[116:119]
	v_mfma_f32_16x16x32_bf16 v[108:111], v[132:135], v[176:179], v[108:111]
	v_mfma_f32_16x16x32_bf16 v[100:103], v[140:143], v[176:179], v[100:103]
	v_mfma_f32_16x16x32_bf16 v[92:95], v[132:135], v[210:213], v[92:95]
	v_mfma_f32_16x16x32_bf16 v[84:87], v[140:143], v[210:213], v[84:87]
	v_mfma_f32_16x16x32_bf16 v[76:79], v[132:135], v[218:221], v[76:79]
	v_mfma_f32_16x16x32_bf16 v[68:71], v[140:143], v[218:221], v[68:71]
	v_mfma_f32_16x16x32_bf16 v[120:123], v[144:147], v[164:167], 0
	v_mfma_f32_16x16x32_bf16 v[112:115], v[156:159], v[164:167], 0
	v_mfma_f32_16x16x32_bf16 v[104:107], v[144:147], v[172:175], 0
	v_mfma_f32_16x16x32_bf16 v[96:99], v[156:159], v[172:175], 0
	v_mfma_f32_16x16x32_bf16 v[88:91], v[144:147], v[180:183], 0
	v_mfma_f32_16x16x32_bf16 v[80:83], v[156:159], v[180:183], 0
	v_mfma_f32_16x16x32_bf16 v[72:75], v[144:147], v[214:217], 0
	v_mfma_f32_16x16x32_bf16 v[64:67], v[156:159], v[214:217], 0
	v_mfma_f32_16x16x32_bf16 v[120:123], v[152:155], v[168:171], v[120:123]
	v_mfma_f32_16x16x32_bf16 v[112:115], v[160:163], v[168:171], v[112:115]
	v_mfma_f32_16x16x32_bf16 v[104:107], v[152:155], v[176:179], v[104:107]
	v_mfma_f32_16x16x32_bf16 v[96:99], v[160:163], v[176:179], v[96:99]
	v_mfma_f32_16x16x32_bf16 v[88:91], v[152:155], v[210:213], v[88:91]
	v_mfma_f32_16x16x32_bf16 v[80:83], v[160:163], v[210:213], v[80:83]
	v_mfma_f32_16x16x32_bf16 v[72:75], v[152:155], v[218:221], v[72:75]
	v_mfma_f32_16x16x32_bf16 v[64:67], v[160:163], v[218:221], v[64:67]
	s_setprio 0
	s_barrier
	ds_read_b128 v[164:167], v208 offset:16384
	ds_read_b128 v[168:171], v208 offset:17408
	ds_read_b128 v[172:175], v208 offset:18432
	ds_read_b128 v[176:179], v208 offset:19456
	ds_read_b128 v[180:183], v208 offset:20480
	ds_read_b128 v[210:213], v208 offset:21504
	ds_read_b128 v[214:217], v208 offset:22528
	ds_read_b128 v[218:221], v208 offset:23552
	s_mov_b32 m0, s50
	s_nop 0
	global_load_lds_dwordx4 v151, s[36:37]
	s_mov_b32 m0, s51
	s_nop 0
	global_load_lds_dwordx4 v199, s[36:37]
	s_add_u32 s4, s36, s47
	s_addc_u32 s5, s37, 0
	s_mov_b32 m0, s61
	s_nop 0
	global_load_lds_dwordx4 v151, s[4:5]
	s_mov_b32 m0, s62
	s_nop 0
	global_load_lds_dwordx4 v199, s[4:5]
	s_mov_b32 m0, s49
	s_nop 0
	global_load_lds_dwordx4 v148, s[40:41]
	s_mov_b32 m0, s63
	s_nop 0
	global_load_lds_dwordx4 v198, s[40:41]
	s_waitcnt vmcnt(8)
	s_waitcnt lgkmcnt(0)
	s_barrier
	s_setprio 1
	v_mfma_f32_16x16x32_bf16 v[60:63], v[128:131], v[164:167], 0
	v_mfma_f32_16x16x32_bf16 v[52:55], v[136:139], v[164:167], 0
	v_mfma_f32_16x16x32_bf16 v[44:47], v[128:131], v[172:175], 0
	v_mfma_f32_16x16x32_bf16 v[36:39], v[136:139], v[172:175], 0
	v_mfma_f32_16x16x32_bf16 v[28:31], v[128:131], v[180:183], 0
	v_mfma_f32_16x16x32_bf16 v[20:23], v[136:139], v[180:183], 0
	v_mfma_f32_16x16x32_bf16 v[12:15], v[128:131], v[214:217], 0
	v_mfma_f32_16x16x32_bf16 v[4:7], v[136:139], v[214:217], 0
	v_mfma_f32_16x16x32_bf16 v[60:63], v[132:135], v[168:171], v[60:63]
	v_mfma_f32_16x16x32_bf16 v[52:55], v[140:143], v[168:171], v[52:55]
	v_mfma_f32_16x16x32_bf16 v[44:47], v[132:135], v[176:179], v[44:47]
	v_mfma_f32_16x16x32_bf16 v[36:39], v[140:143], v[176:179], v[36:39]
	v_mfma_f32_16x16x32_bf16 v[28:31], v[132:135], v[210:213], v[28:31]
	v_mfma_f32_16x16x32_bf16 v[20:23], v[140:143], v[210:213], v[20:23]
	v_mfma_f32_16x16x32_bf16 v[12:15], v[132:135], v[218:221], v[12:15]
	v_mfma_f32_16x16x32_bf16 v[4:7], v[140:143], v[218:221], v[4:7]
	v_mfma_f32_16x16x32_bf16 v[56:59], v[144:147], v[164:167], 0
	v_mfma_f32_16x16x32_bf16 v[48:51], v[156:159], v[164:167], 0
	v_mfma_f32_16x16x32_bf16 v[40:43], v[144:147], v[172:175], 0
	v_mfma_f32_16x16x32_bf16 v[32:35], v[156:159], v[172:175], 0
	v_mfma_f32_16x16x32_bf16 v[24:27], v[144:147], v[180:183], 0
	v_mfma_f32_16x16x32_bf16 v[16:19], v[156:159], v[180:183], 0
	v_mfma_f32_16x16x32_bf16 v[8:11], v[144:147], v[214:217], 0
	v_mfma_f32_16x16x32_bf16 v[0:3], v[156:159], v[214:217], 0
	v_mfma_f32_16x16x32_bf16 v[56:59], v[152:155], v[168:171], v[56:59]
	v_mfma_f32_16x16x32_bf16 v[48:51], v[160:163], v[168:171], v[48:51]
	v_mfma_f32_16x16x32_bf16 v[40:43], v[152:155], v[176:179], v[40:43]
	v_mfma_f32_16x16x32_bf16 v[32:35], v[160:163], v[176:179], v[32:35]
	v_mfma_f32_16x16x32_bf16 v[24:27], v[152:155], v[210:213], v[24:27]
	v_mfma_f32_16x16x32_bf16 v[16:19], v[160:163], v[210:213], v[16:19]
	v_mfma_f32_16x16x32_bf16 v[8:11], v[152:155], v[218:221], v[8:11]
	v_mfma_f32_16x16x32_bf16 v[0:3], v[160:163], v[218:221], v[0:3]
	s_setprio 0
	s_barrier
; #define PG8_STAGE(bufoff, gbase, voff) do { _Pragma("unroll") for (int _i = 0; _i < 2; ++_i) \
;         pg8_dma16((const char*)(gbase), (voff)[_i], ldsb + (unsigned)((bufoff) + _i * 8192)); } while (0)
; #define PG8_LDA(dst, b, h) do { _Pragma("unroll") for (int m = 0; m < 4; ++m) _Pragma("unroll") for (int k = 0; k < 2; ++k) dst[m][k] = *(const PG8_LAS bf16x8*)(lds + PG8_SA(b, h) + aoff + m * 2048 + k * 1024); } while (0)
; #define PG8_LDB(dst, b, h) do { _Pragma("unroll") for (int n = 0; n < 2; ++n) _Pragma("unroll") for (int k = 0; k < 2; ++k) dst[n][k] = *(const PG8_LAS bf16x8*)(lds + PG8_SB(b, h) + boff + n * 2048 + k * 1024); } while (0)
; #define PG8_MMA(ai, bj, At, Bt) do { __builtin_amdgcn_s_setprio(1); _Pragma("unroll") for (int m = 0; m < 4; ++m) _Pragma("unroll") for (int n = 0; n < 2; ++n) _Pragma("unroll") for (int k = 0; k < 2; ++k) \
;         acc[ai][bj][m][n] = __builtin_amdgcn_mfma_f32_16x16x32_bf16(Bt[n][k], At[m][k], acc[ai][bj][m][n], 0, 0, 0); __builtin_amdgcn_s_setprio(0); } while (0)
; #define PG8_WAIT_V(n) asm volatile("s_waitcnt vmcnt(" #n ")" ::: "memory")
; #define PG8_WAIT_L(n) asm volatile("s_waitcnt lgkmcnt(" #n ")" ::: "memory")
; #define PG8_BAR __builtin_amdgcn_s_barrier()
; #define PG8_SCHED __builtin_amdgcn_sched_barrier(0)
; template <class Epi, class Sched, bool ALIGN_EPI = false, bool SP2 = false>
; __device__ __forceinline__ void gemm_phase(PG8_LAS unsigned char* lds, const Gemm g, const Sched& S, const Epi& E) {
;     ...
;             PG8_LDB(B0, 1, 0); PG8_LDB(B1, 1, 1); PG8_SCHED; PG8_LDA(At, 1, 0); PG8_STAGE(PG8_SA(0, 1), a2 + hstep, voffA);
;             PG8_WAIT_V(8); PG8_WAIT_L(0); PG8_BAR; PG8_MMA(0, 0, At, B0); PG8_MMA(0, 1, At, B1); PG8_BAR; PG8_SCHED;
;             PG8_LDA(At, 1, 1); PG8_STAGE(PG8_SB(1, 0), b3, voffB); PG8_STAGE(PG8_SB(1, 1), b3 + hstep, voffB); PG8_STAGE(PG8_SA(1, 0), a3, voffA);
;             PG8_WAIT_V(8); PG8_WAIT_L(0); PG8_BAR; PG8_MMA(1, 0, At, B0); PG8_MMA(1, 1, At, B1); PG8_BAR; PG8_SCHED;
	ds_read_b128 v[128:131], v231
	ds_read_b128 v[132:135], v231 offset:1024
	ds_read_b128 v[136:139], v231 offset:2048
	ds_read_b128 v[140:143], v231 offset:3072
	ds_read_b128 v[144:147], v232
	ds_read_b128 v[152:155], v232 offset:1024
	ds_read_b128 v[156:159], v232 offset:2048
	ds_read_b128 v[160:163], v232 offset:3072
	ds_read_b128 v[164:167], v208 offset:32768
	ds_read_b128 v[168:171], v208 offset:33792
	ds_read_b128 v[172:175], v208 offset:34816
	ds_read_b128 v[176:179], v208 offset:35840
	ds_read_b128 v[180:183], v208 offset:36864
	ds_read_b128 v[210:213], v208 offset:37888
	ds_read_b128 v[214:217], v208 offset:38912
	ds_read_b128 v[218:221], v208 offset:39936
	s_add_u32 s4, s40, s47
	s_addc_u32 s5, s41, 0
	s_mov_b32 m0, s64
	s_nop 0
	global_load_lds_dwordx4 v148, s[4:5]
	s_mov_b32 m0, s65
	s_nop 0
	global_load_lds_dwordx4 v198, s[4:5]
	s_waitcnt vmcnt(8)
	s_waitcnt lgkmcnt(0)
	s_barrier
	s_setprio 1
	v_mfma_f32_16x16x32_bf16 v[124:127], v[128:131], v[164:167], v[124:127]
	v_mfma_f32_16x16x32_bf16 v[116:119], v[136:139], v[164:167], v[116:119]
	v_mfma_f32_16x16x32_bf16 v[108:111], v[128:131], v[172:175], v[108:111]
	v_mfma_f32_16x16x32_bf16 v[100:103], v[136:139], v[172:175], v[100:103]
	v_mfma_f32_16x16x32_bf16 v[92:95], v[128:131], v[180:183], v[92:95]
	v_mfma_f32_16x16x32_bf16 v[84:87], v[136:139], v[180:183], v[84:87]
	v_mfma_f32_16x16x32_bf16 v[76:79], v[128:131], v[214:217], v[76:79]
	v_mfma_f32_16x16x32_bf16 v[68:71], v[136:139], v[214:217], v[68:71]
	v_mfma_f32_16x16x32_bf16 v[124:127], v[132:135], v[168:171], v[124:127]
	v_mfma_f32_16x16x32_bf16 v[116:119], v[140:143], v[168:171], v[116:119]
	v_mfma_f32_16x16x32_bf16 v[108:111], v[132:135], v[176:179], v[108:111]
	v_mfma_f32_16x16x32_bf16 v[100:103], v[140:143], v[176:179], v[100:103]
	v_mfma_f32_16x16x32_bf16 v[92:95], v[132:135], v[210:213], v[92:95]
	v_mfma_f32_16x16x32_bf16 v[84:87], v[140:143], v[210:213], v[84:87]
	v_mfma_f32_16x16x32_bf16 v[76:79], v[132:135], v[218:221], v[76:79]
	v_mfma_f32_16x16x32_bf16 v[68:71], v[140:143], v[218:221], v[68:71]
	v_mfma_f32_16x16x32_bf16 v[120:123], v[144:147], v[164:167], v[120:123]
	v_mfma_f32_16x16x32_bf16 v[112:115], v[156:159], v[164:167], v[112:115]
	v_mfma_f32_16x16x32_bf16 v[104:107], v[144:147], v[172:175], v[104:107]
	v_mfma_f32_16x16x32_bf16 v[96:99], v[156:159], v[172:175], v[96:99]
	v_mfma_f32_16x16x32_bf16 v[88:91], v[144:147], v[180:183], v[88:91]
	v_mfma_f32_16x16x32_bf16 v[80:83], v[156:159], v[180:183], v[80:83]
	v_mfma_f32_16x16x32_bf16 v[72:75], v[144:147], v[214:217], v[72:75]
	v_mfma_f32_16x16x32_bf16 v[64:67], v[156:159], v[214:217], v[64:67]
	v_mfma_f32_16x16x32_bf16 v[120:123], v[152:155], v[168:171], v[120:123]
	v_mfma_f32_16x16x32_bf16 v[112:115], v[160:163], v[168:171], v[112:115]
	v_mfma_f32_16x16x32_bf16 v[104:107], v[152:155], v[176:179], v[104:107]
	v_mfma_f32_16x16x32_bf16 v[96:99], v[160:163], v[176:179], v[96:99]
	v_mfma_f32_16x16x32_bf16 v[88:91], v[152:155], v[210:213], v[88:91]
	v_mfma_f32_16x16x32_bf16 v[80:83], v[160:163], v[210:213], v[80:83]
	v_mfma_f32_16x16x32_bf16 v[72:75], v[152:155], v[218:221], v[72:75]
	v_mfma_f32_16x16x32_bf16 v[64:67], v[160:163], v[218:221], v[64:67]
	s_setprio 0
	s_barrier
	ds_read_b128 v[164:167], v208 offset:49152
	ds_read_b128 v[168:171], v208 offset:50176
	ds_read_b128 v[172:175], v208 offset:51200
	ds_read_b128 v[176:179], v208 offset:52224
	ds_read_b128 v[180:183], v208 offset:53248
	ds_read_b128 v[210:213], v208 offset:54272
	ds_read_b128 v[214:217], v208 offset:55296
	ds_read_b128 v[218:221], v208 offset:56320
	s_add_u32 s4, s36, 0x80
	s_addc_u32 s5, s37, 0
	s_mov_b32 m0, s67
	s_nop 0
	global_load_lds_dwordx4 v151, s[4:5]
	s_mov_b32 m0, s70
	s_nop 0
	global_load_lds_dwordx4 v199, s[4:5]
	s_add_u32 s4, s4, s47
	s_addc_u32 s5, s5, 0
	s_mov_b32 m0, s75
	s_nop 0
	global_load_lds_dwordx4 v151, s[4:5]
	s_mov_b32 m0, s76
	s_nop 0
	global_load_lds_dwordx4 v199, s[4:5]
	s_mov_b32 m0, s71
	s_nop 0
	global_load_lds_dwordx4 v148, s[12:13]
	s_mov_b32 m0, s74
	s_nop 0
	global_load_lds_dwordx4 v198, s[12:13]
	s_add_u32 s72, s72, 0x100
	s_addc_u32 s95, s95, 0
	s_add_u32 vcc_lo, vcc_lo, 0x100
	s_addc_u32 vcc_hi, vcc_hi, 0
	s_add_u32 s10, s10, 0x100
	s_addc_u32 s11, s11, 0
	s_mov_b32 s12, s58
	s_cmp_ge_u32 s58, s60
	s_waitcnt vmcnt(8)
	s_waitcnt lgkmcnt(0)
	s_barrier
	s_setprio 1
	v_mfma_f32_16x16x32_bf16 v[60:63], v[128:131], v[164:167], v[60:63]
	v_mfma_f32_16x16x32_bf16 v[52:55], v[136:139], v[164:167], v[52:55]
	v_mfma_f32_16x16x32_bf16 v[44:47], v[128:131], v[172:175], v[44:47]
	v_mfma_f32_16x16x32_bf16 v[36:39], v[136:139], v[172:175], v[36:39]
	v_mfma_f32_16x16x32_bf16 v[28:31], v[128:131], v[180:183], v[28:31]
	v_mfma_f32_16x16x32_bf16 v[20:23], v[136:139], v[180:183], v[20:23]
	v_mfma_f32_16x16x32_bf16 v[12:15], v[128:131], v[214:217], v[12:15]
	v_mfma_f32_16x16x32_bf16 v[4:7], v[136:139], v[214:217], v[4:7]
	v_mfma_f32_16x16x32_bf16 v[60:63], v[132:135], v[168:171], v[60:63]
	v_mfma_f32_16x16x32_bf16 v[52:55], v[140:143], v[168:171], v[52:55]
	v_mfma_f32_16x16x32_bf16 v[44:47], v[132:135], v[176:179], v[44:47]
	v_mfma_f32_16x16x32_bf16 v[36:39], v[140:143], v[176:179], v[36:39]
	v_mfma_f32_16x16x32_bf16 v[28:31], v[132:135], v[210:213], v[28:31]
	v_mfma_f32_16x16x32_bf16 v[20:23], v[140:143], v[210:213], v[20:23]
	v_mfma_f32_16x16x32_bf16 v[12:15], v[132:135], v[218:221], v[12:15]
	v_mfma_f32_16x16x32_bf16 v[4:7], v[140:143], v[218:221], v[4:7]
	v_mfma_f32_16x16x32_bf16 v[56:59], v[144:147], v[164:167], v[56:59]
	v_mfma_f32_16x16x32_bf16 v[48:51], v[156:159], v[164:167], v[48:51]
	v_mfma_f32_16x16x32_bf16 v[40:43], v[144:147], v[172:175], v[40:43]
	v_mfma_f32_16x16x32_bf16 v[32:35], v[156:159], v[172:175], v[32:35]
	v_mfma_f32_16x16x32_bf16 v[24:27], v[144:147], v[180:183], v[24:27]
	v_mfma_f32_16x16x32_bf16 v[16:19], v[156:159], v[180:183], v[16:19]
	v_mfma_f32_16x16x32_bf16 v[8:11], v[144:147], v[214:217], v[8:11]
	v_mfma_f32_16x16x32_bf16 v[0:3], v[156:159], v[214:217], v[0:3]
	v_mfma_f32_16x16x32_bf16 v[56:59], v[152:155], v[168:171], v[56:59]
	v_mfma_f32_16x16x32_bf16 v[48:51], v[160:163], v[168:171], v[48:51]
	v_mfma_f32_16x16x32_bf16 v[40:43], v[152:155], v[176:179], v[40:43]
	v_mfma_f32_16x16x32_bf16 v[32:35], v[160:163], v[176:179], v[32:35]
	v_mfma_f32_16x16x32_bf16 v[24:27], v[152:155], v[210:213], v[24:27]
	v_mfma_f32_16x16x32_bf16 v[16:19], v[160:163], v[210:213], v[16:19]
	v_mfma_f32_16x16x32_bf16 v[8:11], v[152:155], v[218:221], v[8:11]
	v_mfma_f32_16x16x32_bf16 v[0:3], v[160:163], v[218:221], v[0:3]
	s_setprio 0
	s_barrier
	s_cbranch_scc0 .LBB0_305
	s_branch .Lml_exit2

; #define PG8_BAR __builtin_amdgcn_s_barrier()
; template <class Epi, class Sched, bool ALIGN_EPI = false, bool SP2 = false>
; __device__ __forceinline__ void gemm_phase(PG8_LAS unsigned char* lds, const Gemm g, const Sched& S, const Epi& E) {
;     ...
;         if constexpr (ALIGN_EPI) { if (wr == 0) PG8_BAR; }
;         if constexpr (!Epi::AFTER_DRAIN) { E(acc, cur, wr, wc, fr, fq); S.done(cur); }
;     __device__ __forceinline__ void operator()(const f32x4 (&acc)[2][2][4][2], const Unit& u, int wr, int wc, int fr, int fq) const {
;         if (kind == 0) sc(acc, u, wr, wc, fr, fq);
;         else if (kind == 1) sw(acc, u, wr, wc, fr, fq);
.Lml_exit2:
	s_and_b64 vcc, exec, s[24:25]
	s_cbranch_vccz .LBB0_309
	s_barrier
	s_lshl_b32 s40, s94, 8
	s_cmp_lt_i32 s93, 2
	s_mov_b64 s[10:11], -1
	s_cbranch_scc0 .LBB0_310
